# speedup vs baseline: 1.0248x; 1.0093x over previous
.Lh2_idle:
	s_sub_i32 s4, 0x180, s57
	s_lshl_b32 s5, s4, 1
	s_cmp_gt_i32 s5, s42
	s_cbranch_scc1 .LBB0_96
	v_readlane_b32 s5, v254, 53
	s_add_i32 s33, s5, s57
	s_sub_i32 s33, s33, s4
	s_cmpk_lt_i32 s33, 0x180
	s_cbranch_scc0 .LBB0_96
	s_movk_i32 s7, 0x80
	s_branch .Lh2_tile
.Lh2_top:
	s_movk_i32 s7, 0
.Lh2_tile:
	s_ashr_i32 s4, s33, 31
	s_lshr_b32 s4, s4, 26
	s_add_i32 s4, s33, s4
	s_ashr_i32 s5, s4, 6
	s_and_b32 s4, s4, 0xffc0
	s_sub_i32 s4, s33, s4
	s_lshl_b32 s61, s5, 3
	s_bfe_i32 s5, s4, 0x80000
	s_bfe_u32 s5, s5, 0x3000c
	s_add_i32 s5, s4, s5
	s_bfe_i32 s6, s5, 0x80000
	s_and_b32 s5, s5, 0xf8
	s_sub_i32 s4, s4, s5
	s_sext_i32_i16 s6, s6
	s_sext_i32_i8 s4, s4
	s_add_i32 s61, s61, s4
	s_ashr_i32 s4, s6, 3
	s_mov_b32 s6, -1
	s_lshl_b32 s52, s61, 8
	s_or_b32 s52, s52, s7
	v_mbcnt_lo_u32_b32 v0, s6, 0
	v_mbcnt_hi_u32_b32 v0, s6, v0
	v_add_u32_e32 v128, s43, v0
	s_lshl_b32 s53, s4, 8
	v_bfe_i32 v4, v128, 27, 1
	v_lshlrev_b32_e32 v2, 4, v128
	v_lshrrev_b32_e32 v4, 22, v4
	v_add_u32_e32 v4, v2, v4
	v_and_b32_e32 v4, 0xfffffc00, v4
	v_ashrrev_i32_e32 v3, 31, v128
	v_sub_u32_e32 v4, v2, v4
	v_lshrrev_b32_e32 v3, 26, v3
	v_lshrrev_b32_e32 v5, 4, v4
	v_add_u32_e32 v3, v128, v3
	v_bitop3_b32 v5, v5, v4, 32 bitop3:0x6c
	v_ashrrev_i32_e32 v4, 31, v4
	v_ashrrev_i32_e32 v3, 6, v3
	v_lshrrev_b32_e32 v4, 26, v4
	v_lshlrev_b32_e32 v6, 3, v3
	v_add_u32_e32 v4, v5, v4
	v_ashrrev_i32_e32 v1, 6, v128
	v_and_b32_e32 v6, 0x7ffff0, v6
	v_ashrrev_i32_e32 v4, 6, v4
	v_readfirstlane_b32 s6, v1
	v_add_u32_e32 v6, v4, v6
	v_mul_i32_i24_e32 v4, 64, v4
	s_lshl_b32 s62, s6, 10
	v_sub_u32_e32 v4, v5, v4
	s_movk_i32 s6, 0x1600
	v_lshlrev_b32_e32 v3, 5, v3
	v_ashrrev_i16_sdwa v4, v226, sext(v4) dst_sel:DWORD dst_unused:UNUSED_PAD src0_sel:DWORD src1_sel:BYTE_0
	v_mul_lo_u32 v5, v6, s6
	v_bfe_i32 v4, v4, 0, 16
	v_and_or_b32 v3, v3, 32, v5
	v_add_u32_e32 v2, 0x2000, v2
	v_add_lshl_u32 v129, v3, v4, 1
	v_ashrrev_i32_e32 v3, 31, v2
	v_lshrrev_b32_e32 v3, 22, v3
	v_add_u32_e32 v3, v2, v3
	v_ashrrev_i32_e32 v3, 10, v3
	v_mul_i32_i24_e32 v4, 0x400, v3
	v_sub_u32_e32 v2, v2, v4
	v_lshrrev_b32_e32 v4, 4, v2
	v_bitop3_b32 v2, v4, v2, 32 bitop3:0x6c
	v_ashrrev_i32_e32 v5, 31, v2
	v_lshrrev_b32_e32 v5, 26, v5
	v_lshlrev_b32_e32 v4, 3, v3
	v_add_u32_e32 v5, v2, v5
	v_and_b32_e32 v4, 0x7ffff0, v4
	v_lshrrev_b32_e32 v6, 6, v5
	v_and_b32_e32 v5, 0xc0, v5
	v_add_u32_e32 v4, v6, v4
	v_sub_u32_e32 v2, v2, v5
	s_mul_i32 s36, s4, 0x2c0000
	s_or_b32 s60, s53, 0x80
	s_or_b32 s5, s52, 0x80
	v_lshlrev_b32_e32 v3, 5, v3
	v_ashrrev_i16_sdwa v2, v226, sext(v2) dst_sel:DWORD dst_unused:UNUSED_PAD src0_sel:DWORD src1_sel:BYTE_0
	v_mul_lo_u32 v4, v4, s6
	s_ashr_i32 s37, s36, 31
	v_bfe_i32 v2, v2, 0, 16
	v_and_or_b32 v3, v3, 32, v4
	s_add_u32 s8, s55, s36
	v_add_lshl_u32 v130, v3, v2, 1
	s_addc_u32 s9, s56, s37
	s_add_i32 s63, s62, 0x10000
	s_add_i32 s64, s62, 0x12000
	s_mul_i32 s65, s52, 0x2c00
	v_mov_b32_e32 v2, v129
	v_mov_b32_e32 v3, v130
	s_mov_b32 m0, s63
	s_mul_hi_i32 s66, s52, 0x2c00
	s_add_u32 s10, s80, s65
	s_mul_i32 s4, s60, 0x2c00
	s_addc_u32 s11, s81, s66
	global_load_lds_dwordx4 v2, s[8:9]
	s_mov_b32 m0, s64
	s_add_i32 s67, s62, 0x2000
	s_ashr_i32 s7, s4, 31
	global_load_lds_dwordx4 v3, s[8:9]
	v_mov_b32_e32 v2, v129
	v_mov_b32_e32 v3, v130
	s_mov_b32 m0, s62
	s_add_u32 s6, s55, s4
	s_addc_u32 s7, s56, s7
	global_load_lds_dwordx4 v2, s[10:11]
	s_mov_b32 m0, s67
	s_add_i32 s68, s62, 0x14000
	s_add_i32 s69, s62, 0x16000
	s_mul_hi_i32 s28, s5, 0x2c00
	s_mulk_i32 s5, 0x2c00
	global_load_lds_dwordx4 v3, s[10:11]
	v_mov_b32_e32 v2, v129
	v_mov_b32_e32 v3, v130
	s_mov_b32 m0, s68
	s_add_u32 s4, s80, s5
	s_addc_u32 s5, s81, s28
	global_load_lds_dwordx4 v2, s[6:7]
	s_mov_b32 m0, s69
	s_add_i32 s70, s62, 0x4000
	global_load_lds_dwordx4 v3, s[6:7]
	v_mov_b32_e32 v2, v129
	v_mov_b32_e32 v3, v130
	s_mov_b32 m0, s70
	s_add_i32 s71, s62, 0x6000
	v_ashrrev_i32_e32 v0, 8, v128
	s_mov_b32 m0, s71
	v_cmp_eq_u32_e32 vcc, 1, v0
	s_and_saveexec_b64 s[28:29], vcc
	s_cbranch_execz .Lh2_137
	s_barrier
.Lh2_137:
	s_or_b64 exec, exec, s[28:29]
	v_mov_b32_e32 v196, v129
	v_mov_b32_e32 v2, v130
	s_waitcnt vmcnt(2)
	s_barrier
	s_add_i32 s28, s62, 0x18000
	v_lshl_add_u64 v[4:5], s[8:9], 0, v[196:197]
	v_mov_b32_e32 v3, v197
	v_lshl_add_u64 v[4:5], v[4:5], 0, s[94:95]
	s_mov_b32 m0, s28
	v_lshl_add_u64 v[2:3], s[8:9], 0, v[2:3]
	s_add_i32 s29, s62, 0x1a000
	global_load_lds_dwordx4 v[4:5], off
	v_lshl_add_u64 v[2:3], v[2:3], 0, s[94:95]
	s_mov_b32 m0, s29
	v_mov_b32_e32 v196, v129
	global_load_lds_dwordx4 v[2:3], off
	v_mov_b32_e32 v2, v130
	s_add_i32 s72, s62, 0x8000
	v_lshl_add_u64 v[4:5], s[10:11], 0, v[196:197]
	v_mov_b32_e32 v3, v197
	v_lshl_add_u64 v[4:5], v[4:5], 0, s[94:95]
	s_mov_b32 m0, s72
	v_lshl_add_u64 v[2:3], s[10:11], 0, v[2:3]
	s_add_i32 s73, s62, 0xa000
	global_load_lds_dwordx4 v[4:5], off
	v_lshl_add_u64 v[2:3], v[2:3], 0, s[94:95]
	s_mov_b32 m0, s73
	v_mov_b32_e32 v196, v129
	global_load_lds_dwordx4 v[2:3], off
	v_mov_b32_e32 v2, v130
	s_add_i32 s33, s62, 0x1c000
	v_lshl_add_u64 v[4:5], s[6:7], 0, v[196:197]
	v_mov_b32_e32 v3, v197
	v_lshl_add_u64 v[4:5], v[4:5], 0, s[94:95]
	s_mov_b32 m0, s33
	v_lshl_add_u64 v[2:3], s[6:7], 0, v[2:3]
	s_add_i32 s74, s62, 0x1e000
	global_load_lds_dwordx4 v[4:5], off
	v_lshl_add_u64 v[2:3], v[2:3], 0, s[94:95]
	s_mov_b32 m0, s74
	v_and_b32_e32 v6, 15, v128
	global_load_lds_dwordx4 v[2:3], off
	v_and_b32_e32 v7, 48, v128
	v_lshlrev_b32_e32 v2, 6, v6
	v_lshlrev_b32_e32 v4, 2, v128
	v_or_b32_e32 v3, v2, v7
	v_and_b32_e32 v4, 32, v4
	s_mov_b32 s6, 0x10000
	v_bitop3_b32 v5, v3, s6, v4 bitop3:0xde
	s_mov_b32 s6, 0x14000
	v_lshlrev_b32_e32 v9, 13, v0
	v_lshlrev_b32_e32 v0, 6, v128
	s_waitcnt vmcnt(6)
	v_lshlrev_b32_e32 v1, 12, v1
	v_bitop3_b32 v6, v3, s6, v4 bitop3:0xde
	s_mov_b32 s6, 0x1c000
	v_and_b32_e32 v0, 0x3c0, v0
	v_readlane_b32 s44, v253, 1
	v_and_b32_e32 v1, 0x3000, v1
	v_bitop3_b32 v2, v2, v4, v7 bitop3:0x36
	v_bitop3_b32 v8, v3, s2, v4 bitop3:0xde
	v_bitop3_b32 v3, v3, s6, v4 bitop3:0xde
	v_bitop3_b32 v4, v0, v4, v7 bitop3:0x36
	v_or_b32_e32 v7, 0x800, v9
	v_or_b32_e32 v10, 0x1000, v9
	v_or_b32_e32 v11, 0x1800, v9
	s_add_u32 s36, s54, s36
	v_mov_b32_e32 v0, 0
	v_readlane_b32 s45, v253, 2
	v_readlane_b32 s46, v253, 3
	v_readlane_b32 s47, v253, 4
	v_readlane_b32 s48, v253, 5
	v_readlane_b32 s49, v253, 6
	v_readlane_b32 s50, v253, 7
	v_readlane_b32 s51, v253, 8
	s_addc_u32 s37, s34, s37
	s_mov_b32 s38, -2
	s_add_i32 s76, s62, 0xc000
	s_add_i32 s75, s62, 0xe000
	v_add_u32_e32 v138, v5, v1
	v_add_u32_e32 v134, v2, v9
	v_add_u32_e32 v133, v4, v7
	v_add_u32_e32 v132, v4, v10
	v_add_u32_e32 v131, v4, v11
	v_add_u32_e32 v137, v6, v1
	v_add_u32_e32 v136, v8, v1
	v_add_u32_e32 v135, v3, v1
	s_mov_b64 s[6:7], s[50:51]
	v_mov_b32_e32 v1, v0
	v_mov_b32_e32 v2, v0
	v_mov_b32_e32 v3, v0
	v_mov_b32_e32 v4, v0
	v_mov_b32_e32 v5, v0
	v_mov_b32_e32 v6, v0
	v_mov_b32_e32 v7, v0
	v_mov_b32_e32 v8, v0
	v_mov_b32_e32 v9, v0
	v_mov_b32_e32 v10, v0
	v_mov_b32_e32 v11, v0
	v_mov_b32_e32 v12, v0
	v_mov_b32_e32 v13, v0
	v_mov_b32_e32 v14, v0
	v_mov_b32_e32 v15, v0
	v_mov_b32_e32 v16, v0
	v_mov_b32_e32 v17, v0
	v_mov_b32_e32 v18, v0
	v_mov_b32_e32 v19, v0
	v_mov_b32_e32 v20, v0
	v_mov_b32_e32 v21, v0
	v_mov_b32_e32 v22, v0
	v_mov_b32_e32 v23, v0
	v_mov_b32_e32 v24, v0
	v_mov_b32_e32 v25, v0
	v_mov_b32_e32 v26, v0
	v_mov_b32_e32 v27, v0
	v_mov_b32_e32 v28, v0
	v_mov_b32_e32 v29, v0
	v_mov_b32_e32 v30, v0
	v_mov_b32_e32 v31, v0
	v_mov_b32_e32 v32, v0
	v_mov_b32_e32 v33, v0
	v_mov_b32_e32 v34, v0
	v_mov_b32_e32 v35, v0
	v_mov_b32_e32 v36, v0
	v_mov_b32_e32 v37, v0
	v_mov_b32_e32 v38, v0
	v_mov_b32_e32 v39, v0
	v_mov_b32_e32 v40, v0
	v_mov_b32_e32 v41, v0
	v_mov_b32_e32 v42, v0
	v_mov_b32_e32 v43, v0
	v_mov_b32_e32 v44, v0
	v_mov_b32_e32 v45, v0
	v_mov_b32_e32 v46, v0
	v_mov_b32_e32 v47, v0
	v_mov_b32_e32 v48, v0
	v_mov_b32_e32 v49, v0
	v_mov_b32_e32 v50, v0
	v_mov_b32_e32 v51, v0
	v_mov_b32_e32 v52, v0
	v_mov_b32_e32 v53, v0
	v_mov_b32_e32 v54, v0
	v_mov_b32_e32 v55, v0
	v_mov_b32_e32 v56, v0
	v_mov_b32_e32 v57, v0
	v_mov_b32_e32 v58, v0
	v_mov_b32_e32 v59, v0
	v_mov_b32_e32 v60, v0
	v_mov_b32_e32 v61, v0
	v_mov_b32_e32 v62, v0
	v_mov_b32_e32 v63, v0
	v_mov_b32_e32 v64, v0
	v_mov_b32_e32 v65, v0
	v_mov_b32_e32 v66, v0
	v_mov_b32_e32 v67, v0
	v_mov_b32_e32 v68, v0
	v_mov_b32_e32 v69, v0
	v_mov_b32_e32 v70, v0
	v_mov_b32_e32 v71, v0
	v_mov_b32_e32 v72, v0
	v_mov_b32_e32 v73, v0
	v_mov_b32_e32 v74, v0
	v_mov_b32_e32 v75, v0
	v_mov_b32_e32 v76, v0
	v_mov_b32_e32 v77, v0
	v_mov_b32_e32 v78, v0
	v_mov_b32_e32 v79, v0
	v_mov_b32_e32 v80, v0
	v_mov_b32_e32 v81, v0
	v_mov_b32_e32 v82, v0
	v_mov_b32_e32 v83, v0
	v_mov_b32_e32 v84, v0
	v_mov_b32_e32 v85, v0
	v_mov_b32_e32 v86, v0
	v_mov_b32_e32 v87, v0
	v_mov_b32_e32 v88, v0
	v_mov_b32_e32 v89, v0
	v_mov_b32_e32 v90, v0
	v_mov_b32_e32 v91, v0
	v_mov_b32_e32 v92, v0
	v_mov_b32_e32 v93, v0
	v_mov_b32_e32 v94, v0
	v_mov_b32_e32 v95, v0
	v_mov_b32_e32 v96, v0
	v_mov_b32_e32 v97, v0
	v_mov_b32_e32 v98, v0
	v_mov_b32_e32 v99, v0
	v_mov_b32_e32 v100, v0
	v_mov_b32_e32 v101, v0
	v_mov_b32_e32 v102, v0
	v_mov_b32_e32 v103, v0
	v_mov_b32_e32 v104, v0
	v_mov_b32_e32 v105, v0
	v_mov_b32_e32 v106, v0
	v_mov_b32_e32 v107, v0
	v_mov_b32_e32 v108, v0
	v_mov_b32_e32 v109, v0
	v_mov_b32_e32 v110, v0
	v_mov_b32_e32 v111, v0
	v_mov_b32_e32 v112, v0
	v_mov_b32_e32 v113, v0
	v_mov_b32_e32 v114, v0
	v_mov_b32_e32 v115, v0
	v_mov_b32_e32 v116, v0
	v_mov_b32_e32 v117, v0
	v_mov_b32_e32 v118, v0
	v_mov_b32_e32 v119, v0
	v_mov_b32_e32 v120, v0
	v_mov_b32_e32 v121, v0
	v_mov_b32_e32 v122, v0
	v_mov_b32_e32 v123, v0
	v_mov_b32_e32 v124, v0
	v_mov_b32_e32 v125, v0
	v_mov_b32_e32 v126, v0
	v_mov_b32_e32 v127, v0
	s_mov_b64 s[44:45], 0x20560080
	s_mov_b64 s[46:47], 0xd400100
	s_mov_b64 s[48:49], 0x20400100
	s_mov_b64 s[50:51], 0xd560100
	s_mov_b64 s[90:91], 0x20560100
	s_mov_b64 s[92:93], 0xd400180
	s_mov_b64 s[96:97], 0x20400180
	s_mov_b64 vcc, 0xd560180
	s_barrier
.Lh2_loop:
	ds_read_b128 v[140:143], v138
	ds_read_b128 v[144:147], v138 offset:1024
	ds_read_b128 v[148:151], v138 offset:2048
	ds_read_b128 v[152:155], v138 offset:3072
	s_add_u32 s8, s6, s65
	v_mov_b32_e32 v196, v129
	v_mov_b32_e32 v188, v130
	s_addc_u32 s9, s7, s66
	ds_read_b128 v[156:159], v134
	ds_read_b128 v[160:163], v134 offset:1024
	ds_read_b128 v[164:167], v133
	ds_read_b128 v[168:171], v133 offset:1024
	ds_read_b128 v[172:175], v132
	ds_read_b128 v[176:179], v132 offset:1024
	ds_read_b128 v[180:183], v131
	ds_read_b128 v[184:187], v131 offset:1024
	v_mov_b32_e32 v189, v197
	v_lshl_add_u64 v[190:191], s[8:9], 0, v[196:197]
	s_mov_b32 m0, s76
	v_lshl_add_u64 v[190:191], v[190:191], 0, s[44:45]
	v_lshl_add_u64 v[188:189], s[8:9], 0, v[188:189]
	v_lshl_add_u64 v[188:189], v[188:189], 0, s[44:45]
	s_mov_b32 m0, s75
	s_nop 0
	s_waitcnt lgkmcnt(8)
	s_barrier
	s_waitcnt lgkmcnt(0)
	s_setprio 1
	s_waitcnt lgkmcnt(0)
	v_mfma_f32_16x16x32_bf16 v[124:127], v[140:143], v[156:159], v[124:127]
	v_mfma_f32_16x16x32_bf16 v[120:123], v[148:151], v[156:159], v[120:123]
	v_mfma_f32_16x16x32_bf16 v[116:119], v[140:143], v[164:167], v[116:119]
	v_mfma_f32_16x16x32_bf16 v[112:115], v[148:151], v[164:167], v[112:115]
	v_mfma_f32_16x16x32_bf16 v[108:111], v[140:143], v[172:175], v[108:111]
	v_mfma_f32_16x16x32_bf16 v[104:107], v[148:151], v[172:175], v[104:107]
	v_mfma_f32_16x16x32_bf16 v[100:103], v[140:143], v[180:183], v[100:103]
	v_mfma_f32_16x16x32_bf16 v[96:99], v[148:151], v[180:183], v[96:99]
	v_mfma_f32_16x16x32_bf16 v[124:127], v[144:147], v[160:163], v[124:127]
	v_mfma_f32_16x16x32_bf16 v[120:123], v[152:155], v[160:163], v[120:123]
	v_mfma_f32_16x16x32_bf16 v[116:119], v[144:147], v[168:171], v[116:119]
	v_mfma_f32_16x16x32_bf16 v[112:115], v[152:155], v[168:171], v[112:115]
	v_mfma_f32_16x16x32_bf16 v[108:111], v[144:147], v[176:179], v[108:111]
	v_mfma_f32_16x16x32_bf16 v[104:107], v[152:155], v[176:179], v[104:107]
	v_mfma_f32_16x16x32_bf16 v[100:103], v[144:147], v[184:187], v[100:103]
	v_mfma_f32_16x16x32_bf16 v[96:99], v[152:155], v[184:187], v[96:99]
	s_setprio 0
	s_barrier
	s_add_u32 s10, s6, s36
	v_mov_b32_e32 v196, v129
	v_mov_b32_e32 v210, v130
	s_addc_u32 s11, s7, s37
	ds_read_b128 v[188:191], v137
	ds_read_b128 v[192:195], v137 offset:1024
	ds_read_b128 v[202:205], v137 offset:2048
	ds_read_b128 v[206:209], v137 offset:3072
	v_mov_b32_e32 v211, v197
	v_lshl_add_u64 v[212:213], s[10:11], 0, v[196:197]
	s_mov_b32 m0, s63
	v_lshl_add_u64 v[212:213], v[212:213], 0, s[46:47]
	v_lshl_add_u64 v[210:211], s[10:11], 0, v[210:211]
	global_load_lds_dwordx4 v[212:213], off
	v_lshl_add_u64 v[210:211], v[210:211], 0, s[46:47]
	s_mov_b32 m0, s64
	s_nop 0
	global_load_lds_dwordx4 v[210:211], off
	s_barrier
	s_waitcnt lgkmcnt(0)
	s_setprio 1
	s_waitcnt lgkmcnt(0)
	v_mfma_f32_16x16x32_bf16 v[92:95], v[188:191], v[156:159], v[92:95]
	v_mfma_f32_16x16x32_bf16 v[88:91], v[202:205], v[156:159], v[88:91]
	v_mfma_f32_16x16x32_bf16 v[84:87], v[188:191], v[164:167], v[84:87]
	v_mfma_f32_16x16x32_bf16 v[80:83], v[202:205], v[164:167], v[80:83]
	v_mfma_f32_16x16x32_bf16 v[76:79], v[188:191], v[172:175], v[76:79]
	v_mfma_f32_16x16x32_bf16 v[72:75], v[202:205], v[172:175], v[72:75]
	v_mfma_f32_16x16x32_bf16 v[68:71], v[188:191], v[180:183], v[68:71]
	v_mfma_f32_16x16x32_bf16 v[64:67], v[202:205], v[180:183], v[64:67]
	v_mfma_f32_16x16x32_bf16 v[92:95], v[192:195], v[160:163], v[92:95]
	v_mfma_f32_16x16x32_bf16 v[88:91], v[206:209], v[160:163], v[88:91]
	v_mfma_f32_16x16x32_bf16 v[84:87], v[192:195], v[168:171], v[84:87]
	v_mfma_f32_16x16x32_bf16 v[80:83], v[206:209], v[168:171], v[80:83]
	v_mfma_f32_16x16x32_bf16 v[76:79], v[192:195], v[176:179], v[76:79]
	v_mfma_f32_16x16x32_bf16 v[72:75], v[206:209], v[176:179], v[72:75]
	v_mfma_f32_16x16x32_bf16 v[68:71], v[192:195], v[184:187], v[68:71]
	v_mfma_f32_16x16x32_bf16 v[64:67], v[206:209], v[184:187], v[64:67]
	s_setprio 0
	v_mov_b32_e32 v196, v129
	v_mov_b32_e32 v210, v130
	s_barrier
	v_mov_b32_e32 v211, v197
	v_lshl_add_u64 v[212:213], s[8:9], 0, v[196:197]
	s_mov_b32 m0, s62
	v_lshl_add_u64 v[212:213], v[212:213], 0, s[48:49]
	v_lshl_add_u64 v[210:211], s[8:9], 0, v[210:211]
	global_load_lds_dwordx4 v[212:213], off
	v_lshl_add_u64 v[210:211], v[210:211], 0, s[48:49]
	s_mov_b32 m0, s67
	s_nop 0
	global_load_lds_dwordx4 v[210:211], off
	s_barrier
	s_waitcnt lgkmcnt(0)
	s_setprio 1
	s_waitcnt lgkmcnt(0)
	s_setprio 0
	s_barrier
	v_mov_b32_e32 v196, v129
	v_mov_b32_e32 v140, v130
	v_mov_b32_e32 v141, v197
	v_lshl_add_u64 v[142:143], s[10:11], 0, v[196:197]
	s_mov_b32 m0, s68
	v_lshl_add_u64 v[142:143], v[142:143], 0, s[50:51]
	v_lshl_add_u64 v[140:141], s[10:11], 0, v[140:141]
	global_load_lds_dwordx4 v[142:143], off
	v_lshl_add_u64 v[140:141], v[140:141], 0, s[50:51]
	s_mov_b32 m0, s69
	s_nop 0
	global_load_lds_dwordx4 v[140:141], off
	s_waitcnt vmcnt(6)
	s_barrier
	s_setprio 1
	s_setprio 0
	s_barrier
	ds_read_b128 v[140:143], v136
	ds_read_b128 v[144:147], v136 offset:1024
	ds_read_b128 v[148:151], v136 offset:2048
	ds_read_b128 v[152:155], v136 offset:3072
	v_mov_b32_e32 v196, v129
	v_mov_b32_e32 v188, v130
	ds_read_b128 v[156:159], v134 offset:32768
	ds_read_b128 v[160:163], v134 offset:33792
	ds_read_b128 v[164:167], v133 offset:32768
	ds_read_b128 v[168:171], v133 offset:33792
	ds_read_b128 v[172:175], v132 offset:32768
	ds_read_b128 v[176:179], v132 offset:33792
	ds_read_b128 v[180:183], v131 offset:32768
	ds_read_b128 v[184:187], v131 offset:33792
	v_mov_b32_e32 v189, v197
	v_lshl_add_u64 v[190:191], s[8:9], 0, v[196:197]
	s_mov_b32 m0, s70
	v_lshl_add_u64 v[190:191], v[190:191], 0, s[90:91]
	v_lshl_add_u64 v[188:189], s[8:9], 0, v[188:189]
	v_lshl_add_u64 v[188:189], v[188:189], 0, s[90:91]
	s_mov_b32 m0, s71
	s_nop 0
	s_waitcnt lgkmcnt(8)
	s_barrier
	s_waitcnt lgkmcnt(0)
	s_setprio 1
	s_waitcnt lgkmcnt(0)
	v_mfma_f32_16x16x32_bf16 v[124:127], v[140:143], v[156:159], v[124:127]
	v_mfma_f32_16x16x32_bf16 v[120:123], v[148:151], v[156:159], v[120:123]
	v_mfma_f32_16x16x32_bf16 v[116:119], v[140:143], v[164:167], v[116:119]
	v_mfma_f32_16x16x32_bf16 v[112:115], v[148:151], v[164:167], v[112:115]
	v_mfma_f32_16x16x32_bf16 v[108:111], v[140:143], v[172:175], v[108:111]
	v_mfma_f32_16x16x32_bf16 v[104:107], v[148:151], v[172:175], v[104:107]
	v_mfma_f32_16x16x32_bf16 v[100:103], v[140:143], v[180:183], v[100:103]
	v_mfma_f32_16x16x32_bf16 v[96:99], v[148:151], v[180:183], v[96:99]
	v_mfma_f32_16x16x32_bf16 v[124:127], v[144:147], v[160:163], v[124:127]
	v_mfma_f32_16x16x32_bf16 v[120:123], v[152:155], v[160:163], v[120:123]
	v_mfma_f32_16x16x32_bf16 v[116:119], v[144:147], v[168:171], v[116:119]
	v_mfma_f32_16x16x32_bf16 v[112:115], v[152:155], v[168:171], v[112:115]
	v_mfma_f32_16x16x32_bf16 v[108:111], v[144:147], v[176:179], v[108:111]
	v_mfma_f32_16x16x32_bf16 v[104:107], v[152:155], v[176:179], v[104:107]
	v_mfma_f32_16x16x32_bf16 v[100:103], v[144:147], v[184:187], v[100:103]
	v_mfma_f32_16x16x32_bf16 v[96:99], v[152:155], v[184:187], v[96:99]
	s_setprio 0
	s_barrier
	v_mov_b32_e32 v196, v129
	v_mov_b32_e32 v210, v130
	ds_read_b128 v[188:191], v135
	ds_read_b128 v[192:195], v135 offset:1024
	ds_read_b128 v[202:205], v135 offset:2048
	ds_read_b128 v[206:209], v135 offset:3072
	v_mov_b32_e32 v211, v197
	v_lshl_add_u64 v[212:213], s[10:11], 0, v[196:197]
	s_mov_b32 m0, s28
	v_lshl_add_u64 v[212:213], v[212:213], 0, s[92:93]
	v_lshl_add_u64 v[210:211], s[10:11], 0, v[210:211]
	global_load_lds_dwordx4 v[212:213], off
	v_lshl_add_u64 v[210:211], v[210:211], 0, s[92:93]
	s_mov_b32 m0, s29
	s_nop 0
	global_load_lds_dwordx4 v[210:211], off
	s_barrier
	s_waitcnt lgkmcnt(0)
	s_setprio 1
	s_waitcnt lgkmcnt(0)
	v_mfma_f32_16x16x32_bf16 v[92:95], v[188:191], v[156:159], v[92:95]
	v_mfma_f32_16x16x32_bf16 v[88:91], v[202:205], v[156:159], v[88:91]
	v_mfma_f32_16x16x32_bf16 v[84:87], v[188:191], v[164:167], v[84:87]
	v_mfma_f32_16x16x32_bf16 v[80:83], v[202:205], v[164:167], v[80:83]
	v_mfma_f32_16x16x32_bf16 v[76:79], v[188:191], v[172:175], v[76:79]
	v_mfma_f32_16x16x32_bf16 v[72:75], v[202:205], v[172:175], v[72:75]
	v_mfma_f32_16x16x32_bf16 v[68:71], v[188:191], v[180:183], v[68:71]
	v_mfma_f32_16x16x32_bf16 v[64:67], v[202:205], v[180:183], v[64:67]
	v_mfma_f32_16x16x32_bf16 v[92:95], v[192:195], v[160:163], v[92:95]
	v_mfma_f32_16x16x32_bf16 v[88:91], v[206:209], v[160:163], v[88:91]
	v_mfma_f32_16x16x32_bf16 v[84:87], v[192:195], v[168:171], v[84:87]
	v_mfma_f32_16x16x32_bf16 v[80:83], v[206:209], v[168:171], v[80:83]
	v_mfma_f32_16x16x32_bf16 v[76:79], v[192:195], v[176:179], v[76:79]
	v_mfma_f32_16x16x32_bf16 v[72:75], v[206:209], v[176:179], v[72:75]
	v_mfma_f32_16x16x32_bf16 v[68:71], v[192:195], v[184:187], v[68:71]
	v_mfma_f32_16x16x32_bf16 v[64:67], v[206:209], v[184:187], v[64:67]
	s_setprio 0
	v_mov_b32_e32 v196, v129
	v_mov_b32_e32 v210, v130
	s_barrier
	v_mov_b32_e32 v211, v197
	v_lshl_add_u64 v[212:213], s[8:9], 0, v[196:197]
	s_mov_b32 m0, s72
	v_lshl_add_u64 v[212:213], v[212:213], 0, s[96:97]
	v_lshl_add_u64 v[210:211], s[8:9], 0, v[210:211]
	global_load_lds_dwordx4 v[212:213], off
	v_lshl_add_u64 v[210:211], v[210:211], 0, s[96:97]
	s_mov_b32 m0, s73
	s_nop 0
	global_load_lds_dwordx4 v[210:211], off
	s_barrier
	s_waitcnt lgkmcnt(0)
	s_setprio 1
	s_waitcnt lgkmcnt(0)
	s_setprio 0
	s_barrier
	v_mov_b32_e32 v196, v129
	v_mov_b32_e32 v140, v130
	v_mov_b32_e32 v141, v197
	v_lshl_add_u64 v[142:143], s[10:11], 0, v[196:197]
	s_mov_b32 m0, s33
	v_lshl_add_u64 v[142:143], v[142:143], 0, vcc
	v_lshl_add_u64 v[140:141], s[10:11], 0, v[140:141]
	global_load_lds_dwordx4 v[142:143], off
	v_lshl_add_u64 v[140:141], v[140:141], 0, vcc
	s_mov_b32 m0, s74
	s_nop 0
	global_load_lds_dwordx4 v[140:141], off
	s_waitcnt vmcnt(6)
	s_barrier
	s_setprio 1
	s_setprio 0
	s_add_i32 s38, s38, 2
	s_add_u32 s6, s6, 0x100
	s_addc_u32 s7, s7, 0
	s_cmpk_lt_u32 s38, 0x54
	s_barrier
	s_cbranch_scc1 .Lh2_loop
	s_add_u32 s4, s4, 0x2b80
	s_addc_u32 s5, s5, 0
	s_mov_b32 m0, s76
	ds_read_b128 v[140:143], v138
	ds_read_b128 v[144:147], v138 offset:1024
	ds_read_b128 v[148:151], v138 offset:2048
	ds_read_b128 v[152:155], v138 offset:3072
	ds_read_b128 v[156:159], v134
	ds_read_b128 v[160:163], v134 offset:1024
	ds_read_b128 v[164:167], v133
	ds_read_b128 v[168:171], v133 offset:1024
	ds_read_b128 v[172:175], v132
	ds_read_b128 v[176:179], v132 offset:1024
	ds_read_b128 v[180:183], v131
	ds_read_b128 v[184:187], v131 offset:1024
	s_nop 0
	s_mov_b32 m0, s75
	s_nop 0
	s_barrier
	s_waitcnt lgkmcnt(0)
	s_setprio 1
	s_waitcnt lgkmcnt(0)
	v_mfma_f32_16x16x32_bf16 v[124:127], v[140:143], v[156:159], v[124:127]
	v_mfma_f32_16x16x32_bf16 v[120:123], v[148:151], v[156:159], v[120:123]
	v_mfma_f32_16x16x32_bf16 v[116:119], v[140:143], v[164:167], v[116:119]
	v_mfma_f32_16x16x32_bf16 v[112:115], v[148:151], v[164:167], v[112:115]
	v_mfma_f32_16x16x32_bf16 v[108:111], v[140:143], v[172:175], v[108:111]
	v_mfma_f32_16x16x32_bf16 v[100:103], v[140:143], v[180:183], v[100:103]
	v_mfma_f32_16x16x32_bf16 v[96:99], v[148:151], v[180:183], v[96:99]
	v_mfma_f32_16x16x32_bf16 v[124:127], v[144:147], v[160:163], v[124:127]
	v_mfma_f32_16x16x32_bf16 v[120:123], v[152:155], v[160:163], v[120:123]
	v_mfma_f32_16x16x32_bf16 v[116:119], v[144:147], v[168:171], v[116:119]
	v_mfma_f32_16x16x32_bf16 v[112:115], v[152:155], v[168:171], v[112:115]
	v_mfma_f32_16x16x32_bf16 v[108:111], v[144:147], v[176:179], v[108:111]
	v_mfma_f32_16x16x32_bf16 v[104:107], v[148:151], v[172:175], v[104:107]
	v_mfma_f32_16x16x32_bf16 v[100:103], v[144:147], v[184:187], v[100:103]
	v_mfma_f32_16x16x32_bf16 v[96:99], v[152:155], v[184:187], v[96:99]
	v_mfma_f32_16x16x32_bf16 v[188:191], v[152:155], v[176:179], v[104:107]
	s_setprio 0
	s_barrier
	s_nop 2
	ds_read_b128 v[104:107], v137
	ds_read_b128 v[192:195], v137 offset:1024
	ds_read_b128 v[202:205], v137 offset:2048
	ds_read_b128 v[206:209], v137 offset:3072
	s_barrier
	s_waitcnt lgkmcnt(0)
	s_setprio 1
	s_waitcnt lgkmcnt(0)
	v_mfma_f32_16x16x32_bf16 v[92:95], v[104:107], v[156:159], v[92:95]
	v_mfma_f32_16x16x32_bf16 v[88:91], v[202:205], v[156:159], v[88:91]
	v_mfma_f32_16x16x32_bf16 v[80:83], v[202:205], v[164:167], v[80:83]
	v_mfma_f32_16x16x32_bf16 v[72:75], v[202:205], v[172:175], v[72:75]
	v_mfma_f32_16x16x32_bf16 v[64:67], v[202:205], v[180:183], v[64:67]
	v_mfma_f32_16x16x32_bf16 v[92:95], v[192:195], v[160:163], v[92:95]
	v_mfma_f32_16x16x32_bf16 v[88:91], v[206:209], v[160:163], v[88:91]
	v_mfma_f32_16x16x32_bf16 v[84:87], v[104:107], v[164:167], v[84:87]
	v_mfma_f32_16x16x32_bf16 v[80:83], v[206:209], v[168:171], v[80:83]
	v_mfma_f32_16x16x32_bf16 v[76:79], v[104:107], v[172:175], v[76:79]
	v_mfma_f32_16x16x32_bf16 v[72:75], v[206:209], v[176:179], v[72:75]
	v_mfma_f32_16x16x32_bf16 v[68:71], v[104:107], v[180:183], v[68:71]
	v_mfma_f32_16x16x32_bf16 v[64:67], v[206:209], v[184:187], v[64:67]
	v_mfma_f32_16x16x32_bf16 v[156:159], v[192:195], v[168:171], v[84:87]
	v_mfma_f32_16x16x32_bf16 v[160:163], v[192:195], v[176:179], v[76:79]
	v_mfma_f32_16x16x32_bf16 v[164:167], v[192:195], v[184:187], v[68:71]
	s_setprio 0
	s_barrier
	s_nop 1
	s_waitcnt vmcnt(2)
	s_barrier
	s_waitcnt lgkmcnt(0)
	s_setprio 1
	s_waitcnt lgkmcnt(0)
	s_setprio 0
	s_setprio 1
	s_setprio 0
	s_barrier
	ds_read_b128 v[16:19], v136
	ds_read_b128 v[180:183], v136 offset:1024
	ds_read_b128 v[184:187], v136 offset:2048
	ds_read_b128 v[192:195], v136 offset:3072
	ds_read_b128 v[0:3], v134 offset:32768
	ds_read_b128 v[4:7], v134 offset:33792
	ds_read_b128 v[8:11], v133 offset:32768
	ds_read_b128 v[12:15], v133 offset:33792
	ds_read_b128 v[44:47], v132 offset:32768
	ds_read_b128 v[202:205], v132 offset:33792
	ds_read_b128 v[206:209], v131 offset:32768
	ds_read_b128 v[222:225], v131 offset:33792
	s_waitcnt vmcnt(0)
	s_barrier
	s_waitcnt lgkmcnt(0)
	s_setprio 1
	s_waitcnt lgkmcnt(0)
	v_mfma_f32_16x16x32_bf16 v[28:31], v[16:19], v[0:3], v[124:127]
	v_mfma_f32_16x16x32_bf16 v[52:55], v[180:183], v[4:7], v[28:31]
	v_mfma_f32_16x16x32_bf16 v[28:31], v[184:187], v[0:3], v[120:123]
	v_mfma_f32_16x16x32_bf16 v[104:107], v[192:195], v[4:7], v[28:31]
	v_mfma_f32_16x16x32_bf16 v[28:31], v[16:19], v[8:11], v[116:119]
	v_mfma_f32_16x16x32_bf16 v[68:71], v[180:183], v[12:15], v[28:31]
	v_mfma_f32_16x16x32_bf16 v[28:31], v[184:187], v[8:11], v[112:115]
	v_mfma_f32_16x16x32_bf16 v[116:119], v[192:195], v[12:15], v[28:31]
	v_mfma_f32_16x16x32_bf16 v[28:31], v[16:19], v[44:47], v[108:111]
	v_mfma_f32_16x16x32_bf16 v[76:79], v[180:183], v[202:205], v[28:31]
	v_mfma_f32_16x16x32_bf16 v[28:31], v[184:187], v[44:47], v[188:191]
	v_mfma_f32_16x16x32_bf16 v[108:111], v[192:195], v[202:205], v[28:31]
	v_mfma_f32_16x16x32_bf16 v[28:31], v[16:19], v[206:209], v[100:103]
	v_mfma_f32_16x16x32_bf16 v[84:87], v[180:183], v[222:225], v[28:31]
	v_mfma_f32_16x16x32_bf16 v[28:31], v[184:187], v[206:209], v[96:99]
	v_mfma_f32_16x16x32_bf16 v[96:99], v[192:195], v[222:225], v[28:31]
	s_setprio 0
	s_barrier
	ds_read_b128 v[188:191], v135
	ds_read_b128 v[228:231], v135 offset:1024
	ds_read_b128 v[232:235], v135 offset:2048
	ds_read_b128 v[236:239], v135 offset:3072
	s_waitcnt vmcnt(0)
	s_barrier
	s_waitcnt lgkmcnt(0)
	s_setprio 1
	s_waitcnt lgkmcnt(0)
	v_mfma_f32_16x16x32_bf16 v[28:31], v[188:191], v[0:3], v[92:95]
	v_mfma_f32_16x16x32_bf16 v[0:3], v[232:235], v[0:3], v[88:91]
	v_mfma_f32_16x16x32_bf16 v[28:31], v[228:231], v[4:7], v[28:31]
	v_mfma_f32_16x16x32_bf16 v[0:3], v[236:239], v[4:7], v[0:3]
	v_mfma_f32_16x16x32_bf16 v[4:7], v[188:191], v[8:11], v[156:159]
	v_mfma_f32_16x16x32_bf16 v[36:39], v[228:231], v[12:15], v[4:7]
	v_mfma_f32_16x16x32_bf16 v[4:7], v[232:235], v[8:11], v[80:83]
	v_mfma_f32_16x16x32_bf16 v[4:7], v[236:239], v[12:15], v[4:7]
	v_mfma_f32_16x16x32_bf16 v[8:11], v[188:191], v[44:47], v[160:163]
	v_mfma_f32_16x16x32_bf16 v[12:15], v[188:191], v[206:209], v[164:167]
	v_mfma_f32_16x16x32_bf16 v[40:43], v[228:231], v[202:205], v[8:11]
	v_mfma_f32_16x16x32_bf16 v[8:11], v[232:235], v[44:47], v[72:75]
	v_mfma_f32_16x16x32_bf16 v[44:47], v[228:231], v[222:225], v[12:15]
	v_mfma_f32_16x16x32_bf16 v[12:15], v[232:235], v[206:209], v[64:67]
	v_mfma_f32_16x16x32_bf16 v[8:11], v[236:239], v[202:205], v[8:11]
	v_mfma_f32_16x16x32_bf16 v[12:15], v[236:239], v[222:225], v[12:15]
	s_setprio 0
	s_barrier
	s_barrier
	s_waitcnt lgkmcnt(0)
	s_setprio 1
	s_waitcnt lgkmcnt(0)
	s_setprio 0
	s_setprio 1
	s_setprio 0
	s_movk_i32 s4, 0x100
	v_cmp_gt_u32_e32 vcc, s4, v128
	s_barrier
	s_and_saveexec_b64 s[4:5], vcc
	s_cbranch_execz .Lh2_epi
	s_barrier
.Lh2_epi:
	s_or_b64 exec, exec, s[4:5]
	s_mov_b32 s6, -1
	s_add_i32 s4, s52, 0xfffff000
	v_mbcnt_lo_u32_b32 v128, s6, 0
	v_mbcnt_hi_u32_b32 v128, s6, v128
	v_add_u32_e32 v130, s43, v128
	s_ashr_i32 s4, s4, 10
	s_cmp_gt_i32 s61, 15
	v_lshrrev_b32_e32 v128, 1, v130
	v_ashrrev_i32_e32 v131, 2, v130
	v_and_b32_e32 v128, 0x60, v128
	v_lshrrev_b32_e32 v129, 2, v130
	v_and_b32_e32 v131, 0xffffffc0, v131
	v_and_or_b32 v130, v130, 15, s52
	s_cselect_b32 s4, s4, 8
	v_readlane_b32 s5, v255, 8
	v_and_or_b32 v162, v129, 12, v128
	v_add_u32_e32 v130, v130, v131
	s_add_i32 s4, s4, s5
	v_readlane_b32 s44, v253, 1
	v_or_b32_e32 v148, s53, v162
	v_ashrrev_i32_e32 v131, 31, v130
	s_mul_hi_i32 s5, s4, 0xc000
	s_mul_i32 s4, s4, 0xc000
	v_readlane_b32 s50, v253, 7
	v_ashrrev_i32_e32 v149, 31, v148
	v_readlane_b32 s6, v253, 54
	v_lshlrev_b64 v[136:137], 13, v[130:131]
	v_or_b32_e32 v138, 16, v130
	v_or_b32_e32 v140, 32, v130
	v_or_b32_e32 v142, 48, v130
	v_add_u32_e32 v144, 0x80, v130
	v_add_u32_e32 v146, 0x90, v130
	v_add_u32_e32 v150, 0xa0, v130
	v_add_u32_e32 v130, 0xb0, v130
	v_readlane_b32 s51, v253, 8
	s_add_u32 s4, s50, s4
	v_lshlrev_b64 v[132:133], 2, v[148:149]
	v_readlane_b32 s7, v253, 55
	v_ashrrev_i32_e32 v151, 31, v150
	v_ashrrev_i32_e32 v131, 31, v130
	s_addc_u32 s5, s51, s5
	v_lshl_add_u64 v[134:135], s[6:7], 0, v[132:133]
	v_ashrrev_i32_e32 v139, 31, v138
	v_ashrrev_i32_e32 v141, 31, v140
	v_ashrrev_i32_e32 v143, 31, v142
	v_ashrrev_i32_e32 v145, 31, v144
	v_ashrrev_i32_e32 v147, 31, v146
	v_lshlrev_b64 v[150:151], 13, v[150:151]
	v_lshlrev_b64 v[152:153], 13, v[130:131]
	v_or_b32_e32 v130, 16, v148
	s_add_u32 s4, s4, 0x2f76a000
	v_lshlrev_b64 v[138:139], 13, v[138:139]
	v_lshlrev_b64 v[140:141], 13, v[140:141]
	v_lshlrev_b64 v[142:143], 13, v[142:143]
	v_lshlrev_b64 v[144:145], 13, v[144:145]
	v_lshlrev_b64 v[146:147], 13, v[146:147]
	v_lshl_add_u64 v[202:203], v[134:135], 0, v[150:151]
	v_ashrrev_i32_e32 v131, 31, v130
	v_lshl_add_u64 v[216:217], s[6:7], 0, v[150:151]
	v_or_b32_e32 v150, s60, v162
	v_or_b32_e32 v148, 0x90, v148
	s_addc_u32 s5, s5, 0
	v_lshl_add_u64 v[184:185], v[134:135], 0, v[136:137]
	v_lshl_add_u64 v[186:187], v[134:135], 0, v[138:139]
	v_lshl_add_u64 v[188:189], v[134:135], 0, v[140:141]
	v_lshl_add_u64 v[190:191], v[134:135], 0, v[142:143]
	v_lshl_add_u64 v[192:193], v[134:135], 0, v[144:145]
	v_lshl_add_u64 v[194:195], v[134:135], 0, v[146:147]
	v_lshl_add_u64 v[204:205], v[134:135], 0, v[152:153]
	v_lshlrev_b64 v[134:135], 2, v[130:131]
	v_ashrrev_i32_e32 v151, 31, v150
	v_ashrrev_i32_e32 v149, 31, v148
	v_lshl_add_u64 v[212:213], s[4:5], 0, v[134:135]
	v_lshl_add_u64 v[154:155], s[6:7], 0, v[136:137]
	v_lshl_add_u64 v[156:157], s[6:7], 0, v[138:139]
	v_lshl_add_u64 v[158:159], s[6:7], 0, v[140:141]
	v_lshl_add_u64 v[160:161], s[6:7], 0, v[142:143]
	v_lshl_add_u64 v[164:165], s[6:7], 0, v[144:145]
	v_lshl_add_u64 v[214:215], s[6:7], 0, v[146:147]
	v_lshl_add_u64 v[218:219], s[6:7], 0, v[152:153]
	v_lshlrev_b64 v[150:151], 2, v[150:151]
	v_lshlrev_b64 v[230:231], 2, v[148:149]
	v_lshl_add_u64 v[128:129], s[4:5], 0, v[132:133]
	v_lshl_add_u64 v[130:131], v[154:155], 0, v[134:135]
	v_lshl_add_u64 v[206:207], v[156:157], 0, v[134:135]
	v_lshl_add_u64 v[208:209], v[158:159], 0, v[134:135]
	v_lshl_add_u64 v[210:211], v[160:161], 0, v[134:135]
	v_lshl_add_u64 v[220:221], v[164:165], 0, v[134:135]
	v_lshl_add_u64 v[222:223], v[214:215], 0, v[134:135]
	v_lshl_add_u64 v[224:225], v[216:217], 0, v[134:135]
	v_lshl_add_u64 v[228:229], v[218:219], 0, v[134:135]
	v_lshl_add_u64 v[146:147], v[154:155], 0, v[132:133]
	v_lshl_add_u64 v[144:145], v[156:157], 0, v[132:133]
	v_lshl_add_u64 v[142:143], v[158:159], 0, v[132:133]
	v_lshl_add_u64 v[140:141], v[160:161], 0, v[132:133]
	v_lshl_add_u64 v[138:139], v[164:165], 0, v[132:133]
	v_lshl_add_u64 v[136:137], v[214:215], 0, v[132:133]
	v_lshl_add_u64 v[134:135], v[216:217], 0, v[132:133]
	v_lshl_add_u64 v[132:133], v[218:219], 0, v[132:133]
	v_lshl_add_u64 v[180:181], s[4:5], 0, v[150:151]
	v_lshl_add_u64 v[166:167], v[154:155], 0, v[150:151]
	v_lshl_add_u64 v[168:169], v[156:157], 0, v[150:151]
	v_lshl_add_u64 v[170:171], v[158:159], 0, v[150:151]
	v_lshl_add_u64 v[172:173], v[160:161], 0, v[150:151]
	v_lshl_add_u64 v[174:175], v[164:165], 0, v[150:151]
	v_lshl_add_u64 v[176:177], v[214:215], 0, v[150:151]
	v_lshl_add_u64 v[178:179], v[216:217], 0, v[150:151]
	v_lshl_add_u64 v[182:183], v[218:219], 0, v[150:151]
	v_lshl_add_u64 v[148:149], v[154:155], 0, v[230:231]
	v_lshl_add_u64 v[150:151], v[156:157], 0, v[230:231]
	v_lshl_add_u64 v[152:153], v[158:159], 0, v[230:231]
	v_lshl_add_u64 v[154:155], v[160:161], 0, v[230:231]
	v_lshl_add_u64 v[156:157], v[164:165], 0, v[230:231]
	v_lshl_add_u64 v[158:159], v[214:215], 0, v[230:231]
	v_lshl_add_u64 v[160:161], v[216:217], 0, v[230:231]
	v_lshl_add_u64 v[164:165], v[218:219], 0, v[230:231]
	v_lshl_add_u64 v[162:163], s[4:5], 0, v[230:231]
	v_readlane_b32 s45, v253, 2
	v_readlane_b32 s46, v253, 3
	v_readlane_b32 s47, v253, 4
	v_readlane_b32 s48, v253, 5
	v_readlane_b32 s49, v253, 6
	global_load_dwordx4 v[128:131], v[128:129], off
	global_load_dwordx4 v[212:215], v[212:213], off
	global_load_dwordx4 v[180:183], v[180:181], off
	global_load_dwordx4 v[160:163], v[162:163], off
	global_load_dwordx4 v[148:151], v[146:147], off
	global_load_dwordx4 v[152:155], v[144:145], off
	global_load_dwordx4 v[156:159], v[142:143], off
	global_load_dwordx4 v[164:167], v[140:141], off
	global_load_dwordx4 v[188:191], v[146:147], off offset:64
	global_load_dwordx4 v[192:195], v[144:145], off offset:64
	global_load_dwordx4 v[204:207], v[142:143], off offset:64
	global_load_dwordx4 v[208:211], v[140:141], off offset:64
	global_load_dwordx4 v[168:171], v[146:147], off offset:512
	global_load_dwordx4 v[172:175], v[144:145], off offset:512
	global_load_dwordx4 v[176:179], v[142:143], off offset:512
	global_load_dwordx4 v[184:187], v[140:141], off offset:512
	global_load_dwordx4 v[216:219], v[146:147], off offset:576
	global_load_dwordx4 v[220:223], v[144:145], off offset:576
	global_load_dwordx4 v[228:231], v[142:143], off offset:576
	global_load_dwordx4 v[232:235], v[140:141], off offset:576
	s_waitcnt vmcnt(12)
	v_pk_fma_f32 v[52:53], v[52:53], v[128:129], v[148:149]
	v_pk_fma_f32 v[54:55], v[54:55], v[130:131], v[150:151]
	v_pk_fma_f32 v[68:69], v[68:69], v[128:129], v[152:153]
	v_pk_fma_f32 v[70:71], v[70:71], v[130:131], v[154:155]
	v_pk_fma_f32 v[76:77], v[76:77], v[128:129], v[156:157]
	v_pk_fma_f32 v[78:79], v[78:79], v[130:131], v[158:159]
	v_pk_fma_f32 v[84:85], v[84:85], v[128:129], v[164:165]
	v_pk_fma_f32 v[86:87], v[86:87], v[130:131], v[166:167]
	global_store_dwordx4 v[146:147], v[52:55], off
	global_store_dwordx4 v[144:145], v[68:71], off
	global_store_dwordx4 v[142:143], v[76:79], off
	global_store_dwordx4 v[140:141], v[84:87], off
	s_waitcnt vmcnt(12)
	v_pk_fma_f32 v[104:105], v[104:105], v[212:213], v[188:189]
	v_pk_fma_f32 v[106:107], v[106:107], v[214:215], v[190:191]
	v_pk_fma_f32 v[116:117], v[116:117], v[212:213], v[192:193]
	v_pk_fma_f32 v[118:119], v[118:119], v[214:215], v[194:195]
	v_pk_fma_f32 v[108:109], v[108:109], v[212:213], v[204:205]
	v_pk_fma_f32 v[110:111], v[110:111], v[214:215], v[206:207]
	v_pk_fma_f32 v[96:97], v[96:97], v[212:213], v[208:209]
	v_pk_fma_f32 v[98:99], v[98:99], v[214:215], v[210:211]
	global_store_dwordx4 v[146:147], v[104:107], off offset:64
	global_store_dwordx4 v[144:145], v[116:119], off offset:64
	global_store_dwordx4 v[142:143], v[108:111], off offset:64
	global_store_dwordx4 v[140:141], v[96:99], off offset:64
	s_waitcnt vmcnt(12)
	v_pk_fma_f32 v[28:29], v[28:29], v[180:181], v[168:169]
	v_pk_fma_f32 v[30:31], v[30:31], v[182:183], v[170:171]
	v_pk_fma_f32 v[36:37], v[36:37], v[180:181], v[172:173]
	v_pk_fma_f32 v[38:39], v[38:39], v[182:183], v[174:175]
	v_pk_fma_f32 v[40:41], v[40:41], v[180:181], v[176:177]
	v_pk_fma_f32 v[42:43], v[42:43], v[182:183], v[178:179]
	v_pk_fma_f32 v[44:45], v[44:45], v[180:181], v[184:185]
	v_pk_fma_f32 v[46:47], v[46:47], v[182:183], v[186:187]
	global_store_dwordx4 v[146:147], v[28:31], off offset:512
	global_store_dwordx4 v[144:145], v[36:39], off offset:512
	global_store_dwordx4 v[142:143], v[40:43], off offset:512
	global_store_dwordx4 v[140:141], v[44:47], off offset:512
	s_waitcnt vmcnt(12)
	v_pk_fma_f32 v[0:1], v[0:1], v[160:161], v[216:217]
	v_pk_fma_f32 v[2:3], v[2:3], v[162:163], v[218:219]
	v_pk_fma_f32 v[4:5], v[4:5], v[160:161], v[220:221]
	v_pk_fma_f32 v[6:7], v[6:7], v[162:163], v[222:223]
	v_pk_fma_f32 v[8:9], v[8:9], v[160:161], v[228:229]
	v_pk_fma_f32 v[10:11], v[10:11], v[162:163], v[230:231]
	v_pk_fma_f32 v[12:13], v[12:13], v[160:161], v[232:233]
	v_pk_fma_f32 v[14:15], v[14:15], v[162:163], v[234:235]
	global_store_dwordx4 v[146:147], v[0:3], off offset:576
	global_store_dwordx4 v[144:145], v[4:7], off offset:576
	global_store_dwordx4 v[142:143], v[8:11], off offset:576
	global_store_dwordx4 v[140:141], v[12:15], off offset:576
	s_branch .LBB0_96

.LBB0_134:
	s_andn2_b64 vcc, exec, s[4:5]
	s_cbranch_vccnz .Lh2_idle
	s_sub_i32 s4, 0x180, s57
	s_lshl_b32 s4, s4, 1
	s_cmp_le_i32 s4, s42
	s_cbranch_scc1 .Lh2_top
	s_ashr_i32 s4, s33, 31
	s_lshr_b32 s4, s4, 26
	s_add_i32 s4, s33, s4
	s_ashr_i32 s5, s4, 6
	s_and_b32 s4, s4, 0xffc0
	s_sub_i32 s4, s33, s4
	s_lshl_b32 s61, s5, 3
	s_bfe_i32 s5, s4, 0x80000
	s_bfe_u32 s5, s5, 0x3000c
	s_add_i32 s5, s4, s5
	s_bfe_i32 s6, s5, 0x80000
	s_and_b32 s5, s5, 0xf8
	s_sub_i32 s4, s4, s5
	s_sext_i32_i16 s6, s6
	s_sext_i32_i8 s4, s4
	s_add_i32 s61, s61, s4
	s_ashr_i32 s4, s6, 3
	s_mov_b32 s6, -1
	s_lshl_b32 s52, s61, 8
	v_mbcnt_lo_u32_b32 v0, s6, 0
	v_mbcnt_hi_u32_b32 v0, s6, v0
	v_add_u32_e32 v128, s43, v0
	s_lshl_b32 s53, s4, 8
	v_bfe_i32 v4, v128, 27, 1
	v_lshlrev_b32_e32 v2, 4, v128
	v_lshrrev_b32_e32 v4, 22, v4
	v_add_u32_e32 v4, v2, v4
	v_and_b32_e32 v4, 0xfffffc00, v4
	v_ashrrev_i32_e32 v3, 31, v128
	v_sub_u32_e32 v4, v2, v4
	v_lshrrev_b32_e32 v3, 26, v3
	v_lshrrev_b32_e32 v5, 4, v4
	v_add_u32_e32 v3, v128, v3
	v_bitop3_b32 v5, v5, v4, 32 bitop3:0x6c
	v_ashrrev_i32_e32 v4, 31, v4
	v_ashrrev_i32_e32 v3, 6, v3
	v_lshrrev_b32_e32 v4, 26, v4
	v_lshlrev_b32_e32 v6, 3, v3
	v_add_u32_e32 v4, v5, v4
	v_ashrrev_i32_e32 v1, 6, v128
	v_and_b32_e32 v6, 0x7ffff0, v6
	v_ashrrev_i32_e32 v4, 6, v4
	v_readfirstlane_b32 s6, v1
	v_add_u32_e32 v6, v4, v6
	v_mul_i32_i24_e32 v4, 64, v4
	s_lshl_b32 s62, s6, 10
	v_sub_u32_e32 v4, v5, v4
	s_movk_i32 s6, 0x1600
	v_lshlrev_b32_e32 v3, 5, v3
	v_ashrrev_i16_sdwa v4, v226, sext(v4) dst_sel:DWORD dst_unused:UNUSED_PAD src0_sel:DWORD src1_sel:BYTE_0
	v_mul_lo_u32 v5, v6, s6
	v_bfe_i32 v4, v4, 0, 16
	v_and_or_b32 v3, v3, 32, v5
	v_add_u32_e32 v2, 0x2000, v2
	v_add_lshl_u32 v129, v3, v4, 1
	v_ashrrev_i32_e32 v3, 31, v2
	v_lshrrev_b32_e32 v3, 22, v3
	v_add_u32_e32 v3, v2, v3
	v_ashrrev_i32_e32 v3, 10, v3
	v_mul_i32_i24_e32 v4, 0x400, v3
	v_sub_u32_e32 v2, v2, v4
	v_lshrrev_b32_e32 v4, 4, v2
	v_bitop3_b32 v2, v4, v2, 32 bitop3:0x6c
	v_ashrrev_i32_e32 v5, 31, v2
	v_lshrrev_b32_e32 v5, 26, v5
	v_lshlrev_b32_e32 v4, 3, v3
	v_add_u32_e32 v5, v2, v5
	v_and_b32_e32 v4, 0x7ffff0, v4
	v_lshrrev_b32_e32 v6, 6, v5
	v_and_b32_e32 v5, 0xc0, v5
	v_add_u32_e32 v4, v6, v4
	v_sub_u32_e32 v2, v2, v5
	s_mul_i32 s36, s4, 0x2c0000
	s_or_b32 s60, s53, 0x80
	s_or_b32 s5, s52, 0x80
	v_lshlrev_b32_e32 v3, 5, v3
	v_ashrrev_i16_sdwa v2, v226, sext(v2) dst_sel:DWORD dst_unused:UNUSED_PAD src0_sel:DWORD src1_sel:BYTE_0
	v_mul_lo_u32 v4, v4, s6
	s_ashr_i32 s37, s36, 31
	v_bfe_i32 v2, v2, 0, 16
	v_and_or_b32 v3, v3, 32, v4
	s_add_u32 s8, s55, s36
	v_add_lshl_u32 v130, v3, v2, 1
	s_addc_u32 s9, s56, s37
	s_add_i32 s63, s62, 0x10000
	s_add_i32 s64, s62, 0x12000
	s_mul_i32 s65, s61, 0x2c0000
	v_mov_b32_e32 v2, v129
	v_mov_b32_e32 v3, v130
	s_mov_b32 m0, s63
	s_mul_hi_i32 s66, s52, 0x2c00
	s_add_u32 s10, s80, s65
	s_mul_i32 s4, s60, 0x2c00
	s_addc_u32 s11, s81, s66
	global_load_lds_dwordx4 v2, s[8:9]
	s_mov_b32 m0, s64
	s_add_i32 s67, s62, 0x2000
	s_ashr_i32 s7, s4, 31
	global_load_lds_dwordx4 v3, s[8:9]
	v_mov_b32_e32 v2, v129
	v_mov_b32_e32 v3, v130
	s_mov_b32 m0, s62
	s_add_u32 s6, s55, s4
	s_addc_u32 s7, s56, s7
	global_load_lds_dwordx4 v2, s[10:11]
	s_mov_b32 m0, s67
	s_add_i32 s68, s62, 0x14000
	s_add_i32 s69, s62, 0x16000
	s_mul_hi_i32 s28, s5, 0x2c00
	s_mulk_i32 s5, 0x2c00
	global_load_lds_dwordx4 v3, s[10:11]
	v_mov_b32_e32 v2, v129
	v_mov_b32_e32 v3, v130
	s_mov_b32 m0, s68
	s_add_u32 s4, s80, s5
	s_addc_u32 s5, s81, s28
	global_load_lds_dwordx4 v2, s[6:7]
	s_mov_b32 m0, s69
	s_add_i32 s70, s62, 0x4000
	global_load_lds_dwordx4 v3, s[6:7]
	v_mov_b32_e32 v2, v129
	v_mov_b32_e32 v3, v130
	s_mov_b32 m0, s70
	s_add_i32 s71, s62, 0x6000
	v_ashrrev_i32_e32 v0, 8, v128
	global_load_lds_dwordx4 v2, s[4:5]
	s_mov_b32 m0, s71
	v_cmp_eq_u32_e32 vcc, 1, v0
	global_load_lds_dwordx4 v3, s[4:5]
	s_and_saveexec_b64 s[28:29], vcc
	s_cbranch_execz .LBB0_137
	s_barrier
